# static priority raise for waves 4..7 during the prompt indexer scoring loops (on top of version 94)
# baseline (speedup 1.0000x reference)
;     ...
;     const int b = s & 1, q0 = (s >> 1) * 8, grow0 = b * SEQ + q0, ntile = (q0 + 8 + 31) >> 5;
;     IdxQ qa, qb; idx_load_q(qa, QI, WI, grow0, lane); idx_load_q(qb, QI, WI, grow0 + 4, lane);
;     const size_t kbase = (size_t)(b * SEQ + r) * IDD + kh * 8;
;     IdxKey kn;
;     if (wave < ntile) idx_load_keyb(kn, KIH + kbase + (size_t)wave * 32 * IDD, KIL + kbase + (size_t)wave * 32 * IDD);
;     for (int t = wave; t < ntile; t += NWAVES) {
;         const IdxKey k = kn;
;         if (t + NWAVES < ntile) idx_load_keyb(kn, KIH + kbase + (size_t)(t + NWAVES) * 32 * IDD, KIL + kbase + (size_t)(t + NWAVES) * 32 * IDD);
; __device__ __forceinline__ void mid1_phase(const Params& p, PG8_LAS unsigned char* lds) {
;     ...
;     for (;;) {
;         const unsigned idx = wq_next(ctr, lds);
;         if (idx >= NA + NC_ + NB2) break;
;         if (idx < NA) idx_sample_batch_unit(p, lds, (int)idx);
;         else if (idx < NA + NC_) { const unsigned g = idx - NA; lru_local_unit(p, lds, (int)(g & 7u), (LRU_NGRP - 1 - (int)(g >> 3)) * LRU_GRP); }
;         else { const int s2 = (int)(NB_ - 1 - 2 * (idx - NA - NC_)); idx_prompt_unit(p, lds, s2); __syncthreads(); idx_prompt_unit(p, lds, s2 - 1); }
.LBB0_871:
	s_or_b64 exec, exec, s[0:1]
	s_waitcnt lgkmcnt(0)
	s_barrier
	ds_read_b32 v2, v156
	s_movk_i32 s0, 0x327
	s_waitcnt lgkmcnt(0)
	v_cmp_lt_u32_e32 vcc, s0, v2
	v_readfirstlane_b32 s40, v2
	s_mov_b64 s[0:1], -1
	s_cbranch_vccnz .LBB0_866
	s_cmp_gt_u32 s40, 31
	s_cbranch_scc0 .LBB0_1691
	s_cmpk_gt_u32 s40, 0x127
	s_cbranch_scc0 .LBB0_1553
	v_mov_b32_e32 v2, v0
	s_nop 0
	v_readfirstlane_b32 s0, v2
	s_ashr_i32 s4, s0, 6
	s_lshl_b32 s0, s40, 3
	s_sub_i32 s0, 0x938, s0
	s_and_b32 s10, s0, 0xff8
	s_add_i32 s0, s10, 39
	s_or_b32 s12, s10, 0x1000
	s_lshr_b32 s11, s0, 5
	s_cmp_ge_i32 s4, s11
	v_and_b32_e32 v84, 63, v2
	s_cbranch_scc1 .LBB0_879
	s_cmp_lt_u32 s4, 4
	s_cbranch_scc1 .LidxA_np
	s_setprio 1
.LidxA_np:
	v_and_b32_e32 v3, 31, v2
	v_lshrrev_b32_e32 v5, 5, v84
	v_lshrrev_b32_e32 v4, 1, v84
	v_and_b32_e32 v6, 2, v4
	v_bfe_u32 v7, v2, 4, 1
	v_and_b32_e32 v8, 3, v2
	v_and_or_b32 v8, v4, 4, v8
	v_or3_b32 v9, s12, v7, v6
	v_lshlrev_b32_e32 v10, 10, v9
	v_lshl_add_u32 v10, v8, 7, v10
	v_lshl_add_u32 v10, v5, 4, v10
	v_add_u32_e32 v11, 0x1000, v10
	s_lshl_b32 s1, s12, 5
	v_lshl_add_u32 v12, v5, 6, s1
	global_load_dwordx4 v[18:21], v10, s[64:65]
	global_load_dwordx4 v[22:25], v10, s[64:65] offset:32
	global_load_dwordx4 v[26:29], v10, s[64:65] offset:64
	global_load_dwordx4 v[30:33], v10, s[64:65] offset:96
	global_load_dwordx4 v[34:37], v11, s[64:65]
	global_load_dwordx4 v[38:41], v11, s[64:65] offset:32
	global_load_dwordx4 v[42:45], v11, s[64:65] offset:64
	global_load_dwordx4 v[46:49], v11, s[64:65] offset:96
	global_load_dwordx4 v[50:53], v12, s[66:67]
	global_load_dwordx4 v[54:57], v12, s[66:67] offset:16
	global_load_dwordx4 v[58:61], v12, s[66:67] offset:32
	global_load_dwordx4 v[62:65], v12, s[66:67] offset:48
	global_load_dwordx4 v[66:69], v12, s[66:67] offset:128
	global_load_dwordx4 v[70:73], v12, s[66:67] offset:144
	global_load_dwordx4 v[74:77], v12, s[66:67] offset:160
	global_load_dwordx4 v[78:81], v12, s[66:67] offset:176
	s_add_u32 s6, s34, 0x22f02000
	s_addc_u32 s7, s35, 0
	s_lshl_b32 s1, s4, 12
	v_lshl_add_u32 v94, v3, 7, s1
	v_lshl_add_u32 v94, v5, 4, v94
	s_sub_i32 s3, s11, s4
	s_add_i32 s3, s3, 7
	s_lshr_b32 s3, s3, 3
	global_load_dwordx4 v[102:105], v94, s[6:7]
	global_load_dwordx4 v[106:109], v94, s[6:7] offset:32
	global_load_dwordx4 v[110:113], v94, s[6:7] offset:64
	global_load_dwordx4 v[114:117], v94, s[6:7] offset:96
	s_cmp_lt_u32 s3, 2
	s_cbranch_scc1 .LidxA_pd
	v_add_u32_e32 v95, 0x8000, v94
	global_load_dwordx4 v[118:121], v95, s[6:7]
	global_load_dwordx4 v[122:125], v95, s[6:7] offset:32
	global_load_dwordx4 v[126:129], v95, s[6:7] offset:64
	global_load_dwordx4 v[130:133], v95, s[6:7] offset:96
	s_cmp_lt_u32 s3, 3
	s_cbranch_scc1 .LidxA_pd
	v_add_u32_e32 v95, 0x10000, v94
	global_load_dwordx4 v[134:137], v95, s[6:7]
	global_load_dwordx4 v[138:141], v95, s[6:7] offset:32
	global_load_dwordx4 v[142:145], v95, s[6:7] offset:64
	global_load_dwordx4 v[146:149], v95, s[6:7] offset:96
	s_cmp_lt_u32 s3, 4
	s_cbranch_scc1 .LidxA_pd
	v_add_u32_e32 v95, 0x18000, v94
	global_load_dwordx4 v[160:163], v95, s[6:7]
	global_load_dwordx4 v[164:167], v95, s[6:7] offset:32
	global_load_dwordx4 v[168:171], v95, s[6:7] offset:64
	global_load_dwordx4 v[172:175], v95, s[6:7] offset:96

; __device__ __forceinline__ void idx_tile(const IdxQ& q, const IdxKey& k, float (&s)[2]) {
;     f32x16 acc;
; #pragma unroll
;     for (int i = 0; i < 16; ++i) acc[i] = 0.f;
; #pragma unroll
;     for (int ks = 0; ks < 4; ++ks) {
;         acc = __builtin_amdgcn_mfma_f32_32x32x16_bf16(q.hi[ks], k.hi[ks], acc, 0, 0, 0);
;         if (IDX_SPLIT == 3) { acc = __builtin_amdgcn_mfma_f32_32x32x16_bf16(q.hi[ks], k.lo[ks], acc, 0, 0, 0); acc = __builtin_amdgcn_mfma_f32_32x32x16_bf16(q.lo[ks], k.hi[ks], acc, 0, 0, 0); }
;     }
; #pragma unroll
;     for (int e = 0; e < 2; ++e) {
;         float t = 0.f;
; #pragma unroll
;         for (int i = 0; i < 8; ++i) t += fmaxf(acc[e * 8 + i] * IDX_SCALE, 0.f) * q.w[e * 8 + i];
;         s[e] = t;
;     }
;     ...
;         float sa[2], sb[2]; idx_tile(qa, k, sa); idx_tile(qb, k, sb);
;         const int col = t * 32 + r;
;         sc[(2 * kh) * SCP_LD + col] = sa[0]; sc[(2 * kh + 1) * SCP_LD + col] = sa[1];
;         sc[(4 + 2 * kh) * SCP_LD + col] = sb[0]; sc[(5 + 2 * kh) * SCP_LD + col] = sb[1];
.LidxA_nr_3:
	s_nop 8
	v_mul_f32_e32 v82, 0x3e000000, v2
	v_max_f32_e32 v82, 0, v82
	v_fma_f32 v88, v66, v82, 0
	v_mul_f32_e32 v83, 0x3e000000, v3
	v_max_f32_e32 v83, 0, v83
	v_fmac_f32_e32 v88, v67, v83
	v_mul_f32_e32 v82, 0x3e000000, v4
	v_max_f32_e32 v82, 0, v82
	v_fmac_f32_e32 v88, v68, v82
	v_mul_f32_e32 v83, 0x3e000000, v5
	v_max_f32_e32 v83, 0, v83
	v_fmac_f32_e32 v88, v69, v83
	v_mul_f32_e32 v82, 0x3e000000, v6
	v_max_f32_e32 v82, 0, v82
	v_fmac_f32_e32 v88, v70, v82
	v_mul_f32_e32 v83, 0x3e000000, v7
	v_max_f32_e32 v83, 0, v83
	v_fmac_f32_e32 v88, v71, v83
	v_mul_f32_e32 v82, 0x3e000000, v8
	v_max_f32_e32 v82, 0, v82
	v_fmac_f32_e32 v88, v72, v82
	v_mul_f32_e32 v83, 0x3e000000, v9
	v_max_f32_e32 v83, 0, v83
	v_fmac_f32_e32 v88, v73, v83
	v_mul_f32_e32 v82, 0x3e000000, v10
	v_max_f32_e32 v82, 0, v82
	v_fma_f32 v89, v74, v82, 0
	v_mul_f32_e32 v83, 0x3e000000, v11
	v_max_f32_e32 v83, 0, v83
	v_fmac_f32_e32 v89, v75, v83
	v_mul_f32_e32 v82, 0x3e000000, v12
	v_max_f32_e32 v82, 0, v82
	v_fmac_f32_e32 v89, v76, v82
	v_mul_f32_e32 v83, 0x3e000000, v13
	v_max_f32_e32 v83, 0, v83
	v_fmac_f32_e32 v89, v77, v83
	v_mul_f32_e32 v82, 0x3e000000, v14
	v_max_f32_e32 v82, 0, v82
	v_fmac_f32_e32 v89, v78, v82
	v_mul_f32_e32 v83, 0x3e000000, v15
	v_max_f32_e32 v83, 0, v83
	v_fmac_f32_e32 v89, v79, v83
	v_mul_f32_e32 v82, 0x3e000000, v16
	v_max_f32_e32 v82, 0, v82
	v_fmac_f32_e32 v89, v80, v82
	v_mul_f32_e32 v83, 0x3e000000, v17
	v_max_f32_e32 v83, 0, v83
	v_fmac_f32_e32 v89, v81, v83
	v_add_u32_e32 v93, 0xffff0000, v92
	ds_write_b32 v93, v86
	v_add_u32_e32 v93, 0xffff4000, v92
	ds_write_b32 v93, v87
	ds_write2st64_b32 v92, v88, v89 offset1:64
	v_add_u32_e32 v92, 0x400, v92
	s_add_i32 s5, s5, 1
	s_cmp_lt_u32 s5, s3
	s_cbranch_scc0 .LidxA_done
	s_branch .LidxA_slot_0
.LidxA_done:
	s_setprio 0

;     ...
;     const int b = s & 1, q0 = (s >> 1) * 8, grow0 = b * SEQ + q0, ntile = (q0 + 8 + 31) >> 5;
;     IdxQ qa, qb; idx_load_q(qa, QI, WI, grow0, lane); idx_load_q(qb, QI, WI, grow0 + 4, lane);
;     const size_t kbase = (size_t)(b * SEQ + r) * IDD + kh * 8;
;     IdxKey kn;
;     if (wave < ntile) idx_load_keyb(kn, KIH + kbase + (size_t)wave * 32 * IDD, KIL + kbase + (size_t)wave * 32 * IDD);
;     for (int t = wave; t < ntile; t += NWAVES) {
;         const IdxKey k = kn;
;         if (t + NWAVES < ntile) idx_load_keyb(kn, KIH + kbase + (size_t)(t + NWAVES) * 32 * IDD, KIL + kbase + (size_t)(t + NWAVES) * 32 * IDD);
.LBB0_1212:
	s_add_i32 s0, s4, s12
	s_ashr_i32 s1, s0, 31
	s_lshl_b64 s[0:1], s[0:1], 9
	v_readlane_b32 s3, v238, 3
	s_add_u32 s0, s3, s0
	v_readlane_b32 s3, v238, 4
	s_addc_u32 s1, s3, s1
	v_mov_b32_e32 v3, v68
	v_lshlrev_b32_e32 v4, 3, v84
	global_store_dwordx2 v4, v[2:3], s[0:1]
	v_mov_b32_e32 v2, v0
	s_barrier
	s_nop 0
	v_readfirstlane_b32 s0, v2
	s_ashr_i32 s0, s0, 6
	s_cmp_ge_i32 s0, s11
	v_and_b32_e32 v84, 63, v2
	s_cbranch_scc1 .LBB0_1217
	s_cmp_lt_u32 s0, 4
	s_cbranch_scc1 .LidxB_np
	s_setprio 1
.LidxB_np:
	v_and_b32_e32 v3, 31, v2
	v_lshrrev_b32_e32 v5, 5, v84
	v_lshrrev_b32_e32 v4, 1, v84
	v_and_b32_e32 v6, 2, v4
	v_bfe_u32 v7, v2, 4, 1
	v_and_b32_e32 v8, 3, v2
	v_and_or_b32 v8, v4, 4, v8
	v_or3_b32 v9, s10, v7, v6
	v_lshlrev_b32_e32 v10, 10, v9
	v_lshl_add_u32 v10, v8, 7, v10
	v_lshl_add_u32 v10, v5, 4, v10
	v_add_u32_e32 v11, 0x1000, v10
	s_lshl_b32 s1, s10, 5
	v_lshl_add_u32 v12, v5, 6, s1
	global_load_dwordx4 v[18:21], v10, s[64:65]
	global_load_dwordx4 v[22:25], v10, s[64:65] offset:32
	global_load_dwordx4 v[26:29], v10, s[64:65] offset:64
	global_load_dwordx4 v[30:33], v10, s[64:65] offset:96
	global_load_dwordx4 v[34:37], v11, s[64:65]
	global_load_dwordx4 v[38:41], v11, s[64:65] offset:32
	global_load_dwordx4 v[42:45], v11, s[64:65] offset:64
	global_load_dwordx4 v[46:49], v11, s[64:65] offset:96
	global_load_dwordx4 v[50:53], v12, s[66:67]
	global_load_dwordx4 v[54:57], v12, s[66:67] offset:16
	global_load_dwordx4 v[58:61], v12, s[66:67] offset:32
	global_load_dwordx4 v[62:65], v12, s[66:67] offset:48
	global_load_dwordx4 v[66:69], v12, s[66:67] offset:128
	global_load_dwordx4 v[70:73], v12, s[66:67] offset:144
	global_load_dwordx4 v[74:77], v12, s[66:67] offset:160
	global_load_dwordx4 v[78:81], v12, s[66:67] offset:176
	s_add_u32 s6, s34, 0x22e82000
	s_addc_u32 s7, s35, 0
	s_lshl_b32 s1, s0, 12
	v_lshl_add_u32 v94, v3, 7, s1
	v_lshl_add_u32 v94, v5, 4, v94
	s_sub_i32 s3, s11, s0
	s_add_i32 s3, s3, 7
	s_lshr_b32 s3, s3, 3
	global_load_dwordx4 v[102:105], v94, s[6:7]
	global_load_dwordx4 v[106:109], v94, s[6:7] offset:32
	global_load_dwordx4 v[110:113], v94, s[6:7] offset:64
	global_load_dwordx4 v[114:117], v94, s[6:7] offset:96
	s_cmp_lt_u32 s3, 2
	s_cbranch_scc1 .LidxB_pd
	v_add_u32_e32 v95, 0x8000, v94
	global_load_dwordx4 v[118:121], v95, s[6:7]
	global_load_dwordx4 v[122:125], v95, s[6:7] offset:32
	global_load_dwordx4 v[126:129], v95, s[6:7] offset:64
	global_load_dwordx4 v[130:133], v95, s[6:7] offset:96
	s_cmp_lt_u32 s3, 3
	s_cbranch_scc1 .LidxB_pd
	v_add_u32_e32 v95, 0x10000, v94
	global_load_dwordx4 v[134:137], v95, s[6:7]
	global_load_dwordx4 v[138:141], v95, s[6:7] offset:32
	global_load_dwordx4 v[142:145], v95, s[6:7] offset:64
	global_load_dwordx4 v[146:149], v95, s[6:7] offset:96
	s_cmp_lt_u32 s3, 4
	s_cbranch_scc1 .LidxB_pd
	v_add_u32_e32 v95, 0x18000, v94
	global_load_dwordx4 v[160:163], v95, s[6:7]
	global_load_dwordx4 v[164:167], v95, s[6:7] offset:32
	global_load_dwordx4 v[168:171], v95, s[6:7] offset:64
	global_load_dwordx4 v[172:175], v95, s[6:7] offset:96

; #define PG8_LAS __attribute__((address_space(3)))
; __device__ __forceinline__ unsigned fkey(float f) { const unsigned u = __float_as_uint(f); return (u & 0x80000000u) ? ~u : (u | 0x80000000u); }
; __device__ __forceinline__ void idx_tile(const IdxQ& q, const IdxKey& k, float (&s)[2]) {
;     f32x16 acc;
; #pragma unroll
;     for (int i = 0; i < 16; ++i) acc[i] = 0.f;
; #pragma unroll
;     for (int ks = 0; ks < 4; ++ks) {
;         acc = __builtin_amdgcn_mfma_f32_32x32x16_bf16(q.hi[ks], k.hi[ks], acc, 0, 0, 0);
;         if (IDX_SPLIT == 3) { acc = __builtin_amdgcn_mfma_f32_32x32x16_bf16(q.hi[ks], k.lo[ks], acc, 0, 0, 0); acc = __builtin_amdgcn_mfma_f32_32x32x16_bf16(q.lo[ks], k.hi[ks], acc, 0, 0, 0); }
;     }
; #pragma unroll
;     for (int e = 0; e < 2; ++e) {
;         float t = 0.f;
; #pragma unroll
;         for (int i = 0; i < 8; ++i) t += fmaxf(acc[e * 8 + i] * IDX_SCALE, 0.f) * q.w[e * 8 + i];
;         s[e] = t;
;     }
;     ...
;     const int nj = __builtin_amdgcn_readfirstlane((n + 63) >> 6), ng = (nj + 7) >> 3;
;     const PG8_LAS float* pl = sc + lane;
; #pragma unroll
;     for (int j = 0; j < NJ; ++j) { const unsigned k = fkey(pl[j * 64]); v[j] = (lane < n - j * 64) ? k : 0u; }
.LidxB_nr_3:
	s_nop 8
	v_mul_f32_e32 v82, 0x3e000000, v2
	v_max_f32_e32 v82, 0, v82
	v_fma_f32 v88, v66, v82, 0
	v_mul_f32_e32 v83, 0x3e000000, v3
	v_max_f32_e32 v83, 0, v83
	v_fmac_f32_e32 v88, v67, v83
	v_mul_f32_e32 v82, 0x3e000000, v4
	v_max_f32_e32 v82, 0, v82
	v_fmac_f32_e32 v88, v68, v82
	v_mul_f32_e32 v83, 0x3e000000, v5
	v_max_f32_e32 v83, 0, v83
	v_fmac_f32_e32 v88, v69, v83
	v_mul_f32_e32 v82, 0x3e000000, v6
	v_max_f32_e32 v82, 0, v82
	v_fmac_f32_e32 v88, v70, v82
	v_mul_f32_e32 v83, 0x3e000000, v7
	v_max_f32_e32 v83, 0, v83
	v_fmac_f32_e32 v88, v71, v83
	v_mul_f32_e32 v82, 0x3e000000, v8
	v_max_f32_e32 v82, 0, v82
	v_fmac_f32_e32 v88, v72, v82
	v_mul_f32_e32 v83, 0x3e000000, v9
	v_max_f32_e32 v83, 0, v83
	v_fmac_f32_e32 v88, v73, v83
	v_mul_f32_e32 v82, 0x3e000000, v10
	v_max_f32_e32 v82, 0, v82
	v_fma_f32 v89, v74, v82, 0
	v_mul_f32_e32 v83, 0x3e000000, v11
	v_max_f32_e32 v83, 0, v83
	v_fmac_f32_e32 v89, v75, v83
	v_mul_f32_e32 v82, 0x3e000000, v12
	v_max_f32_e32 v82, 0, v82
	v_fmac_f32_e32 v89, v76, v82
	v_mul_f32_e32 v83, 0x3e000000, v13
	v_max_f32_e32 v83, 0, v83
	v_fmac_f32_e32 v89, v77, v83
	v_mul_f32_e32 v82, 0x3e000000, v14
	v_max_f32_e32 v82, 0, v82
	v_fmac_f32_e32 v89, v78, v82
	v_mul_f32_e32 v83, 0x3e000000, v15
	v_max_f32_e32 v83, 0, v83
	v_fmac_f32_e32 v89, v79, v83
	v_mul_f32_e32 v82, 0x3e000000, v16
	v_max_f32_e32 v82, 0, v82
	v_fmac_f32_e32 v89, v80, v82
	v_mul_f32_e32 v83, 0x3e000000, v17
	v_max_f32_e32 v83, 0, v83
	v_fmac_f32_e32 v89, v81, v83
	v_add_u32_e32 v93, 0xffff0000, v92
	ds_write_b32 v93, v86
	v_add_u32_e32 v93, 0xffff4000, v92
	ds_write_b32 v93, v87
	ds_write2st64_b32 v92, v88, v89 offset1:64
	v_add_u32_e32 v92, 0x400, v92
	s_add_i32 s5, s5, 1
	s_cmp_lt_u32 s5, s3
	s_cbranch_scc0 .LidxB_done
	s_branch .LidxB_slot_0
.LidxB_done:
	s_setprio 0
.LBB0_1217:
	s_lshl_b32 s1, s0, 14
	s_add_i32 s1, s1, 0
	v_lshl_add_u32 v58, v84, 2, s1
	s_waitcnt lgkmcnt(0)
	s_barrier
	ds_read2st64_b32 v[4:5], v58 offset1:1
	s_add_i32 s4, s0, s10
	ds_read2st64_b32 v[6:7], v58 offset0:2 offset1:3
	ds_read2st64_b32 v[10:11], v58 offset0:4 offset1:5
	ds_read2st64_b32 v[12:13], v58 offset0:6 offset1:7
	s_sub_i32 s1, s4, 63
	s_add_i32 s3, s4, 0xffffff41
	s_waitcnt lgkmcnt(3)
	v_not_b32_e32 v2, v4
	v_or_b32_e32 v3, 0x80000000, v4
	v_cmp_gt_i32_e32 vcc, 0, v4
	v_or_b32_e32 v4, 0x80000000, v5
	s_waitcnt lgkmcnt(2)
	v_and_b32_e32 v9, 0x7fffffff, v6
	v_cndmask_b32_e32 v2, v3, v2, vcc
	v_cmp_ge_i32_e32 vcc, s4, v84
	v_and_b32_e32 v8, 0x7fffffff, v7
	v_pk_add_f32 v[8:9], v[8:9], 0 neg_lo:[1,1] neg_hi:[1,1]
	v_cndmask_b32_e32 v3, 0, v2, vcc
	v_not_b32_e32 v2, v5
	v_cmp_gt_i32_e32 vcc, 0, v5
	s_add_i32 s0, s4, 64
	s_ashr_i32 s5, s0, 6
	v_cndmask_b32_e32 v2, v4, v2, vcc
	v_cmp_gt_i32_e32 vcc, s1, v84
	v_xor_b32_e32 v4, -1, v7
	s_add_i32 s1, s4, 0xffffff81
	v_cndmask_b32_e32 v5, 0, v2, vcc
	v_cmp_gt_i32_e32 vcc, 0, v7
	v_xor_b32_e32 v2, -1, v6
	s_waitcnt lgkmcnt(1)
	v_and_b32_e32 v7, 0x7fffffff, v10
	v_cndmask_b32_e32 v4, v8, v4, vcc
	v_cmp_gt_i32_e32 vcc, 0, v6
	v_and_b32_e32 v6, 0x7fffffff, v11
	v_pk_add_f32 v[6:7], v[6:7], 0 neg_lo:[1,1] neg_hi:[1,1]
	v_cndmask_b32_e32 v2, v9, v2, vcc
	v_cmp_gt_i32_e32 vcc, s1, v84
	v_xor_b32_e32 v9, -1, v11
	s_add_i32 s1, s4, 0xffffff01
	v_cndmask_b32_e32 v8, 0, v2, vcc
	v_cmp_gt_i32_e32 vcc, s3, v84
	v_xor_b32_e32 v2, -1, v10
	s_add_i32 s3, s4, 0xfffffec1
	v_cndmask_b32_e32 v4, 0, v4, vcc
	v_cmp_gt_i32_e32 vcc, 0, v11
	s_waitcnt lgkmcnt(0)
	v_and_b32_e32 v11, 0x7fffffff, v12
	s_add_i32 s0, s5, 7
	v_cndmask_b32_e32 v6, v6, v9, vcc
	v_cmp_gt_i32_e32 vcc, 0, v10
	v_and_b32_e32 v10, 0x7fffffff, v13
	v_xor_b32_e32 v9, -1, v13
	v_cndmask_b32_e32 v2, v7, v2, vcc
	v_cmp_gt_i32_e32 vcc, s1, v84
	v_pk_add_f32 v[10:11], v[10:11], 0 neg_lo:[1,1] neg_hi:[1,1]
	s_add_i32 s1, s4, 0xfffffe81
	v_cndmask_b32_e32 v7, 0, v2, vcc
	v_cmp_gt_i32_e32 vcc, s3, v84
	s_add_i32 s3, s4, 0xfffffe41
	s_ashr_i32 s10, s0, 3
	v_cndmask_b32_e32 v2, 0, v6, vcc
	v_cmp_gt_i32_e32 vcc, 0, v13
	v_xor_b32_e32 v6, -1, v12
	s_nop 0
	v_cndmask_b32_e32 v13, v10, v9, vcc
	v_cmp_gt_i32_e32 vcc, 0, v12
	s_nop 1
	v_cndmask_b32_e32 v6, v11, v6, vcc
	ds_read2st64_b32 v[10:11], v58 offset0:8 offset1:9
	v_cmp_gt_i32_e32 vcc, s1, v84
	ds_read2st64_b32 v[14:15], v58 offset0:10 offset1:11
	ds_read2st64_b32 v[18:19], v58 offset0:12 offset1:13
	ds_read2st64_b32 v[20:21], v58 offset0:14 offset1:15
	v_cndmask_b32_e32 v9, 0, v6, vcc
	v_cmp_gt_i32_e32 vcc, s3, v84
	s_waitcnt lgkmcnt(3)
	v_and_b32_e32 v12, 0x7fffffff, v11
	v_xor_b32_e32 v17, -1, v11
	v_cndmask_b32_e32 v6, 0, v13, vcc
	v_and_b32_e32 v13, 0x7fffffff, v10
	v_pk_add_f32 v[12:13], v[12:13], 0 neg_lo:[1,1] neg_hi:[1,1]
	v_cmp_gt_i32_e32 vcc, 0, v11
	v_xor_b32_e32 v16, -1, v10
	s_add_i32 s1, s4, 0xfffffe01
	v_cndmask_b32_e32 v11, v12, v17, vcc
	v_cmp_gt_i32_e32 vcc, 0, v10
	s_add_i32 s3, s4, 0xfffffdc1
	s_waitcnt lgkmcnt(2)
	v_xor_b32_e32 v17, -1, v15
	v_cndmask_b32_e32 v10, v13, v16, vcc
	v_cmp_gt_i32_e32 vcc, s1, v84
	v_xor_b32_e32 v13, -1, v14
	s_add_i32 s1, s4, 0xfffffd81
	v_cndmask_b32_e32 v16, 0, v10, vcc
	v_cmp_gt_i32_e32 vcc, s3, v84
	v_and_b32_e32 v10, 0x7fffffff, v15
	s_add_i32 s3, s4, 0xfffffd41
	v_cndmask_b32_e32 v12, 0, v11, vcc
	v_and_b32_e32 v11, 0x7fffffff, v14
	v_pk_add_f32 v[10:11], v[10:11], 0 neg_lo:[1,1] neg_hi:[1,1]
	v_cmp_gt_i32_e32 vcc, 0, v15
	s_waitcnt lgkmcnt(1)
	v_and_b32_e32 v23, 0x7fffffff, v18
	v_and_b32_e32 v22, 0x7fffffff, v19
	v_cndmask_b32_e32 v10, v10, v17, vcc
	v_cmp_gt_i32_e32 vcc, 0, v14
	v_pk_add_f32 v[22:23], v[22:23], 0 neg_lo:[1,1] neg_hi:[1,1]
	s_waitcnt lgkmcnt(0)
; #define PG8_LAS __attribute__((address_space(3)))
; __device__ __forceinline__ unsigned fkey(float f) { const unsigned u = __float_as_uint(f); return (u & 0x80000000u) ? ~u : (u | 0x80000000u); }
;     ...
;     const int nj = __builtin_amdgcn_readfirstlane((n + 63) >> 6), ng = (nj + 7) >> 3;
;     const PG8_LAS float* pl = sc + lane;
; #pragma unroll
;     for (int j = 0; j < NJ; ++j) { const unsigned k = fkey(pl[j * 64]); v[j] = (lane < n - j * 64) ? k : 0u; }
	v_xor_b32_e32 v17, -1, v21
	v_cndmask_b32_e32 v11, v11, v13, vcc
	v_cmp_gt_i32_e32 vcc, s1, v84
	v_xor_b32_e32 v13, -1, v19
	s_add_i32 s1, s4, 0xfffffd01
	v_cndmask_b32_e32 v15, 0, v11, vcc
	v_cmp_gt_i32_e32 vcc, s3, v84
	s_add_i32 s3, s4, 0xfffffcc1
	s_nop 0
	v_cndmask_b32_e32 v11, 0, v10, vcc
	v_cmp_gt_i32_e32 vcc, 0, v19
	v_xor_b32_e32 v10, -1, v18
	v_and_b32_e32 v19, 0x7fffffff, v20
	v_cndmask_b32_e32 v13, v22, v13, vcc
	v_cmp_gt_i32_e32 vcc, 0, v18
	v_and_b32_e32 v18, 0x7fffffff, v21
	v_pk_add_f32 v[18:19], v[18:19], 0 neg_lo:[1,1] neg_hi:[1,1]
	v_cndmask_b32_e32 v10, v23, v10, vcc
	v_cmp_gt_i32_e32 vcc, s1, v84
	s_add_i32 s1, s4, 0xfffffc81
	s_nop 0
	v_cndmask_b32_e32 v14, 0, v10, vcc
	v_cmp_gt_i32_e32 vcc, s3, v84
	s_add_i32 s3, s4, 0xfffffc41
	s_nop 0
	v_cndmask_b32_e32 v10, 0, v13, vcc
	v_cmp_gt_i32_e32 vcc, 0, v21
	v_xor_b32_e32 v13, -1, v20
	s_nop 0
	v_cndmask_b32_e32 v21, v18, v17, vcc
	v_cmp_gt_i32_e32 vcc, 0, v20
	s_nop 1
	v_cndmask_b32_e32 v13, v19, v13, vcc
	ds_read2st64_b32 v[18:19], v58 offset0:16 offset1:17
	v_cmp_gt_i32_e32 vcc, s1, v84
	ds_read2st64_b32 v[22:23], v58 offset0:18 offset1:19
	ds_read2st64_b32 v[26:27], v58 offset0:20 offset1:21
	ds_read2st64_b32 v[28:29], v58 offset0:22 offset1:23
	v_cndmask_b32_e32 v17, 0, v13, vcc
	v_cmp_gt_i32_e32 vcc, s3, v84
	s_waitcnt lgkmcnt(3)
	v_and_b32_e32 v20, 0x7fffffff, v19
	v_xor_b32_e32 v25, -1, v19
	v_cndmask_b32_e32 v13, 0, v21, vcc
	v_and_b32_e32 v21, 0x7fffffff, v18
	v_pk_add_f32 v[20:21], v[20:21], 0 neg_lo:[1,1] neg_hi:[1,1]
	v_cmp_gt_i32_e32 vcc, 0, v19
	v_xor_b32_e32 v24, -1, v18
	s_add_i32 s1, s4, 0xfffffc01
	v_cndmask_b32_e32 v19, v20, v25, vcc
	v_cmp_gt_i32_e32 vcc, 0, v18
	s_add_i32 s3, s4, 0xfffffbc1
	s_waitcnt lgkmcnt(2)
	v_xor_b32_e32 v25, -1, v23
	v_cndmask_b32_e32 v18, v21, v24, vcc
	v_cmp_gt_i32_e32 vcc, s1, v84
	v_xor_b32_e32 v21, -1, v22
	s_add_i32 s1, s4, 0xfffffb81
	v_cndmask_b32_e32 v24, 0, v18, vcc
	v_cmp_gt_i32_e32 vcc, s3, v84
	v_and_b32_e32 v18, 0x7fffffff, v23
	s_add_i32 s3, s4, 0xfffffb41
	v_cndmask_b32_e32 v20, 0, v19, vcc
	v_and_b32_e32 v19, 0x7fffffff, v22
	v_pk_add_f32 v[18:19], v[18:19], 0 neg_lo:[1,1] neg_hi:[1,1]
	v_cmp_gt_i32_e32 vcc, 0, v23
	s_waitcnt lgkmcnt(1)
	v_and_b32_e32 v31, 0x7fffffff, v26
	v_and_b32_e32 v30, 0x7fffffff, v27
	v_cndmask_b32_e32 v18, v18, v25, vcc
	v_cmp_gt_i32_e32 vcc, 0, v22
	v_pk_add_f32 v[30:31], v[30:31], 0 neg_lo:[1,1] neg_hi:[1,1]
	s_waitcnt lgkmcnt(0)
	v_xor_b32_e32 v25, -1, v29
	v_cndmask_b32_e32 v19, v19, v21, vcc
	v_cmp_gt_i32_e32 vcc, s1, v84
	v_xor_b32_e32 v21, -1, v27
	s_add_i32 s1, s4, 0xfffffb01
	v_cndmask_b32_e32 v23, 0, v19, vcc
	v_cmp_gt_i32_e32 vcc, s3, v84
	s_add_i32 s3, s4, 0xfffffac1
	s_nop 0
	v_cndmask_b32_e32 v19, 0, v18, vcc
	v_cmp_gt_i32_e32 vcc, 0, v27
	v_xor_b32_e32 v18, -1, v26
	v_and_b32_e32 v27, 0x7fffffff, v28
	v_cndmask_b32_e32 v21, v30, v21, vcc
	v_cmp_gt_i32_e32 vcc, 0, v26
	v_and_b32_e32 v26, 0x7fffffff, v29
	v_pk_add_f32 v[26:27], v[26:27], 0 neg_lo:[1,1] neg_hi:[1,1]
	v_cndmask_b32_e32 v18, v31, v18, vcc
	v_cmp_gt_i32_e32 vcc, s1, v84
	s_add_i32 s1, s4, 0xfffffa81
	s_nop 0
	v_cndmask_b32_e32 v22, 0, v18, vcc
	v_cmp_gt_i32_e32 vcc, s3, v84
	s_add_i32 s3, s4, 0xfffffa41
	s_nop 0
	v_cndmask_b32_e32 v18, 0, v21, vcc
	v_cmp_gt_i32_e32 vcc, 0, v29
	v_xor_b32_e32 v21, -1, v28
	s_nop 0
	v_cndmask_b32_e32 v29, v26, v25, vcc
	v_cmp_gt_i32_e32 vcc, 0, v28
	s_nop 1
	v_cndmask_b32_e32 v21, v27, v21, vcc
	ds_read2st64_b32 v[26:27], v58 offset0:24 offset1:25
	v_cmp_gt_i32_e32 vcc, s1, v84
	ds_read2st64_b32 v[30:31], v58 offset0:26 offset1:27
	ds_read2st64_b32 v[34:35], v58 offset0:28 offset1:29
	ds_read2st64_b32 v[36:37], v58 offset0:30 offset1:31
	v_cndmask_b32_e32 v25, 0, v21, vcc
	v_cmp_gt_i32_e32 vcc, s3, v84
	s_waitcnt lgkmcnt(3)
	v_and_b32_e32 v28, 0x7fffffff, v27
	v_xor_b32_e32 v33, -1, v27
	v_cndmask_b32_e32 v21, 0, v29, vcc
	v_and_b32_e32 v29, 0x7fffffff, v26
	v_pk_add_f32 v[28:29], v[28:29], 0 neg_lo:[1,1] neg_hi:[1,1]
	v_cmp_gt_i32_e32 vcc, 0, v27
	v_xor_b32_e32 v32, -1, v26
	s_add_i32 s1, s4, 0xfffffa01
	v_cndmask_b32_e32 v27, v28, v33, vcc
	v_cmp_gt_i32_e32 vcc, 0, v26
	s_add_i32 s3, s4, 0xfffff9c1
	s_waitcnt lgkmcnt(2)
	v_xor_b32_e32 v33, -1, v31
	v_cndmask_b32_e32 v26, v29, v32, vcc
	v_cmp_gt_i32_e32 vcc, s1, v84
	v_xor_b32_e32 v29, -1, v30
	s_add_i32 s1, s4, 0xfffff981
	v_cndmask_b32_e32 v32, 0, v26, vcc
	v_cmp_gt_i32_e32 vcc, s3, v84
	v_and_b32_e32 v26, 0x7fffffff, v31
	s_add_i32 s3, s4, 0xfffff941
	v_cndmask_b32_e32 v28, 0, v27, vcc
	v_and_b32_e32 v27, 0x7fffffff, v30
	v_pk_add_f32 v[26:27], v[26:27], 0 neg_lo:[1,1] neg_hi:[1,1]
	v_cmp_gt_i32_e32 vcc, 0, v31
	s_waitcnt lgkmcnt(1)
	v_and_b32_e32 v39, 0x7fffffff, v34
	v_and_b32_e32 v38, 0x7fffffff, v35
	v_cndmask_b32_e32 v26, v26, v33, vcc
	v_cmp_gt_i32_e32 vcc, 0, v30
	v_pk_add_f32 v[38:39], v[38:39], 0 neg_lo:[1,1] neg_hi:[1,1]
	s_waitcnt lgkmcnt(0)
	v_xor_b32_e32 v33, -1, v37
	v_cndmask_b32_e32 v27, v27, v29, vcc
	v_cmp_gt_i32_e32 vcc, s1, v84
	v_xor_b32_e32 v29, -1, v35
	s_add_i32 s1, s4, 0xfffff901
	v_cndmask_b32_e32 v31, 0, v27, vcc
	v_cmp_gt_i32_e32 vcc, s3, v84
	s_add_i32 s3, s4, 0xfffff8c1
	s_nop 0
	v_cndmask_b32_e32 v27, 0, v26, vcc
	v_cmp_gt_i32_e32 vcc, 0, v35
	v_xor_b32_e32 v26, -1, v34
	v_and_b32_e32 v35, 0x7fffffff, v36
	v_cndmask_b32_e32 v29, v38, v29, vcc
	v_cmp_gt_i32_e32 vcc, 0, v34
	v_and_b32_e32 v34, 0x7fffffff, v37
	v_pk_add_f32 v[34:35], v[34:35], 0 neg_lo:[1,1] neg_hi:[1,1]
	v_cndmask_b32_e32 v26, v39, v26, vcc
	v_cmp_gt_i32_e32 vcc, s1, v84
	s_add_i32 s1, s4, 0xfffff881
	s_nop 0
	v_cndmask_b32_e32 v30, 0, v26, vcc
	v_cmp_gt_i32_e32 vcc, s3, v84
	s_add_i32 s3, s4, 0xfffff841
	s_nop 0
	v_cndmask_b32_e32 v26, 0, v29, vcc
	v_cmp_gt_i32_e32 vcc, 0, v37
	v_xor_b32_e32 v29, -1, v36
	s_nop 0
	v_cndmask_b32_e32 v37, v34, v33, vcc
	v_cmp_gt_i32_e32 vcc, 0, v36
	s_nop 1
	v_cndmask_b32_e32 v29, v35, v29, vcc
	ds_read2st64_b32 v[34:35], v58 offset0:32 offset1:33
	v_cmp_gt_i32_e32 vcc, s1, v84
	ds_read2st64_b32 v[38:39], v58 offset0:34 offset1:35
	ds_read2st64_b32 v[42:43], v58 offset0:36 offset1:37
	ds_read2st64_b32 v[44:45], v58 offset0:38 offset1:39
	v_cndmask_b32_e32 v33, 0, v29, vcc
	v_cmp_gt_i32_e32 vcc, s3, v84
	s_waitcnt lgkmcnt(3)
; #define PG8_LAS __attribute__((address_space(3)))
; __device__ __forceinline__ unsigned fkey(float f) { const unsigned u = __float_as_uint(f); return (u & 0x80000000u) ? ~u : (u | 0x80000000u); }
;     ...
;     const PG8_LAS float* pl = sc + lane;
; #pragma unroll
;     for (int j = 0; j < NJ; ++j) { const unsigned k = fkey(pl[j * 64]); v[j] = (lane < n - j * 64) ? k : 0u; }
	v_and_b32_e32 v36, 0x7fffffff, v35
	v_xor_b32_e32 v41, -1, v35
	v_cndmask_b32_e32 v29, 0, v37, vcc
	v_and_b32_e32 v37, 0x7fffffff, v34
	v_pk_add_f32 v[36:37], v[36:37], 0 neg_lo:[1,1] neg_hi:[1,1]
	v_cmp_gt_i32_e32 vcc, 0, v35
	v_xor_b32_e32 v40, -1, v34
	s_add_i32 s1, s4, 0xfffff801
	v_cndmask_b32_e32 v35, v36, v41, vcc
	v_cmp_gt_i32_e32 vcc, 0, v34
	s_add_i32 s3, s4, 0xfffff7c1
	s_waitcnt lgkmcnt(2)
	v_xor_b32_e32 v41, -1, v39
	v_cndmask_b32_e32 v34, v37, v40, vcc
	v_cmp_gt_i32_e32 vcc, s1, v84
	v_xor_b32_e32 v37, -1, v38
	s_add_i32 s1, s4, 0xfffff781
	v_cndmask_b32_e32 v40, 0, v34, vcc
	v_cmp_gt_i32_e32 vcc, s3, v84
	v_and_b32_e32 v34, 0x7fffffff, v39
	s_add_i32 s3, s4, 0xfffff741
	v_cndmask_b32_e32 v36, 0, v35, vcc
	v_and_b32_e32 v35, 0x7fffffff, v38
	v_pk_add_f32 v[34:35], v[34:35], 0 neg_lo:[1,1] neg_hi:[1,1]
	v_cmp_gt_i32_e32 vcc, 0, v39
	s_waitcnt lgkmcnt(1)
	v_and_b32_e32 v47, 0x7fffffff, v42
	v_and_b32_e32 v46, 0x7fffffff, v43
	v_cndmask_b32_e32 v34, v34, v41, vcc
	v_cmp_gt_i32_e32 vcc, 0, v38
	v_pk_add_f32 v[46:47], v[46:47], 0 neg_lo:[1,1] neg_hi:[1,1]
	s_waitcnt lgkmcnt(0)
	v_xor_b32_e32 v41, -1, v45
	v_cndmask_b32_e32 v35, v35, v37, vcc
	v_cmp_gt_i32_e32 vcc, s1, v84
	v_xor_b32_e32 v37, -1, v43
	s_add_i32 s1, s4, 0xfffff701
	v_cndmask_b32_e32 v39, 0, v35, vcc
	v_cmp_gt_i32_e32 vcc, s3, v84
	s_add_i32 s3, s4, 0xfffff6c1
	s_nop 0
	v_cndmask_b32_e32 v35, 0, v34, vcc
	v_cmp_gt_i32_e32 vcc, 0, v43
	v_xor_b32_e32 v34, -1, v42
	v_and_b32_e32 v43, 0x7fffffff, v44
	v_cndmask_b32_e32 v37, v46, v37, vcc
	v_cmp_gt_i32_e32 vcc, 0, v42
	v_and_b32_e32 v42, 0x7fffffff, v45
	v_pk_add_f32 v[42:43], v[42:43], 0 neg_lo:[1,1] neg_hi:[1,1]
	v_cndmask_b32_e32 v34, v47, v34, vcc
	v_cmp_gt_i32_e32 vcc, s1, v84
	s_add_i32 s1, s4, 0xfffff681
	s_nop 0
	v_cndmask_b32_e32 v38, 0, v34, vcc
	v_cmp_gt_i32_e32 vcc, s3, v84
	s_add_i32 s3, s4, 0xfffff641
	s_nop 0
	v_cndmask_b32_e32 v34, 0, v37, vcc
	v_cmp_gt_i32_e32 vcc, 0, v45
	v_xor_b32_e32 v37, -1, v44
	s_nop 0
	v_cndmask_b32_e32 v45, v42, v41, vcc
	v_cmp_gt_i32_e32 vcc, 0, v44
	s_nop 1
	v_cndmask_b32_e32 v37, v43, v37, vcc
	ds_read2st64_b32 v[42:43], v58 offset0:40 offset1:41
	v_cmp_gt_i32_e32 vcc, s1, v84
	ds_read2st64_b32 v[46:47], v58 offset0:42 offset1:43
	ds_read2st64_b32 v[50:51], v58 offset0:44 offset1:45
	ds_read2st64_b32 v[52:53], v58 offset0:46 offset1:47
	v_cndmask_b32_e32 v41, 0, v37, vcc
	v_cmp_gt_i32_e32 vcc, s3, v84
	s_waitcnt lgkmcnt(3)
	v_and_b32_e32 v44, 0x7fffffff, v43
	v_xor_b32_e32 v49, -1, v43
	v_cndmask_b32_e32 v37, 0, v45, vcc
	v_and_b32_e32 v45, 0x7fffffff, v42
	v_pk_add_f32 v[44:45], v[44:45], 0 neg_lo:[1,1] neg_hi:[1,1]
	v_cmp_gt_i32_e32 vcc, 0, v43
	v_xor_b32_e32 v48, -1, v42
	s_add_i32 s1, s4, 0xfffff601
	v_cndmask_b32_e32 v43, v44, v49, vcc
	v_cmp_gt_i32_e32 vcc, 0, v42
	s_add_i32 s3, s4, 0xfffff5c1
	s_waitcnt lgkmcnt(2)
	v_xor_b32_e32 v49, -1, v47
	v_cndmask_b32_e32 v42, v45, v48, vcc
	v_cmp_gt_i32_e32 vcc, s1, v84
	v_xor_b32_e32 v45, -1, v46
	s_add_i32 s1, s4, 0xfffff581
	v_cndmask_b32_e32 v48, 0, v42, vcc
	v_cmp_gt_i32_e32 vcc, s3, v84
	v_and_b32_e32 v42, 0x7fffffff, v47
	s_add_i32 s3, s4, 0xfffff541
	v_cndmask_b32_e32 v44, 0, v43, vcc
	v_and_b32_e32 v43, 0x7fffffff, v46
	v_pk_add_f32 v[42:43], v[42:43], 0 neg_lo:[1,1] neg_hi:[1,1]
	v_cmp_gt_i32_e32 vcc, 0, v47
	s_waitcnt lgkmcnt(1)
	v_and_b32_e32 v55, 0x7fffffff, v50
	v_and_b32_e32 v54, 0x7fffffff, v51
	v_cndmask_b32_e32 v42, v42, v49, vcc
	v_cmp_gt_i32_e32 vcc, 0, v46
	v_pk_add_f32 v[54:55], v[54:55], 0 neg_lo:[1,1] neg_hi:[1,1]
	s_waitcnt lgkmcnt(0)
	v_xor_b32_e32 v49, -1, v53
	v_cndmask_b32_e32 v43, v43, v45, vcc
	v_cmp_gt_i32_e32 vcc, s1, v84
	v_xor_b32_e32 v45, -1, v51
	s_add_i32 s1, s4, 0xfffff501
	v_cndmask_b32_e32 v47, 0, v43, vcc
	v_cmp_gt_i32_e32 vcc, s3, v84
	s_add_i32 s3, s4, 0xfffff4c1
	s_nop 0
	v_cndmask_b32_e32 v43, 0, v42, vcc
	v_cmp_gt_i32_e32 vcc, 0, v51
	v_xor_b32_e32 v42, -1, v50
	v_and_b32_e32 v51, 0x7fffffff, v52
	v_cndmask_b32_e32 v45, v54, v45, vcc
	v_cmp_gt_i32_e32 vcc, 0, v50
	v_and_b32_e32 v50, 0x7fffffff, v53
	v_pk_add_f32 v[50:51], v[50:51], 0 neg_lo:[1,1] neg_hi:[1,1]
	v_cndmask_b32_e32 v42, v55, v42, vcc
	v_cmp_gt_i32_e32 vcc, s1, v84
	s_add_i32 s1, s4, 0xfffff481
	s_nop 0
	v_cndmask_b32_e32 v46, 0, v42, vcc
	v_cmp_gt_i32_e32 vcc, s3, v84
	s_add_i32 s3, s4, 0xfffff441
	s_nop 0
	v_cndmask_b32_e32 v42, 0, v45, vcc
	v_cmp_gt_i32_e32 vcc, 0, v53
	v_xor_b32_e32 v45, -1, v52
	s_nop 0
	v_cndmask_b32_e32 v53, v50, v49, vcc
	v_cmp_gt_i32_e32 vcc, 0, v52
	s_nop 1
	v_cndmask_b32_e32 v45, v51, v45, vcc
	ds_read2st64_b32 v[50:51], v58 offset0:48 offset1:49
	v_cmp_gt_i32_e32 vcc, s1, v84
	ds_read2st64_b32 v[54:55], v58 offset0:50 offset1:51
	ds_read2st64_b32 v[60:61], v58 offset0:52 offset1:53
	ds_read2st64_b32 v[62:63], v58 offset0:54 offset1:55
	v_cndmask_b32_e32 v49, 0, v45, vcc
	v_cmp_gt_i32_e32 vcc, s3, v84
	s_waitcnt lgkmcnt(3)
; __device__ __forceinline__ unsigned fkey(float f) { const unsigned u = __float_as_uint(f); return (u & 0x80000000u) ? ~u : (u | 0x80000000u); }
;     ...
;     for (int j = 0; j < NJ; ++j) { const unsigned k = fkey(pl[j * 64]); v[j] = (lane < n - j * 64) ? k : 0u; }
;     unsigned T = 1u; int need = 1 << 30;
;     if (n > TOPK) {
;         unsigned prefix = 0u; bool exact;
;         if (NG >= 8 && ng > 7) exact = bit_search<(NG >= 8 ? 8 : NG), NJ, BITLO>(v, prefix);
;         else if (NG >= 7 && ng > 6) exact = bit_search<(NG >= 7 ? 7 : NG), NJ, BITLO>(v, prefix);
;         else if (NG >= 6 && ng > 5) exact = bit_search<(NG >= 6 ? 6 : NG), NJ, BITLO>(v, prefix);
;         else if (NG >= 5 && ng > 4) exact = bit_search<(NG >= 5 ? 5 : NG), NJ, BITLO>(v, prefix);
;         else if (NG >= 4 && ng > 3) exact = bit_search<(NG >= 4 ? 4 : NG), NJ, BITLO>(v, prefix);
;         else if (NG >= 3 && ng > 2) exact = bit_search<(NG >= 3 ? 3 : NG), NJ, BITLO>(v, prefix);
;         else if (NG >= 2 && ng > 1) exact = bit_search<(NG >= 2 ? 2 : NG), NJ, BITLO>(v, prefix);
;         else exact = bit_search<1, NJ, BITLO>(v, prefix);
	v_and_b32_e32 v52, 0x7fffffff, v51
	v_xor_b32_e32 v57, -1, v51
	v_cndmask_b32_e32 v45, 0, v53, vcc
	v_and_b32_e32 v53, 0x7fffffff, v50
	v_pk_add_f32 v[52:53], v[52:53], 0 neg_lo:[1,1] neg_hi:[1,1]
	v_cmp_gt_i32_e32 vcc, 0, v51
	v_xor_b32_e32 v56, -1, v50
	s_add_i32 s1, s4, 0xfffff401
	v_cndmask_b32_e32 v51, v52, v57, vcc
	v_cmp_gt_i32_e32 vcc, 0, v50
	s_add_i32 s3, s4, 0xfffff3c1
	s_waitcnt lgkmcnt(2)
	v_xor_b32_e32 v57, -1, v55
	v_cndmask_b32_e32 v50, v53, v56, vcc
	v_cmp_gt_i32_e32 vcc, s1, v84
	v_xor_b32_e32 v53, -1, v54
	s_add_i32 s1, s4, 0xfffff381
	v_cndmask_b32_e32 v56, 0, v50, vcc
	v_cmp_gt_i32_e32 vcc, s3, v84
	v_and_b32_e32 v50, 0x7fffffff, v55
	s_add_i32 s3, s4, 0xfffff341
	v_cndmask_b32_e32 v52, 0, v51, vcc
	v_and_b32_e32 v51, 0x7fffffff, v54
	v_pk_add_f32 v[50:51], v[50:51], 0 neg_lo:[1,1] neg_hi:[1,1]
	v_cmp_gt_i32_e32 vcc, 0, v55
	s_waitcnt lgkmcnt(1)
	v_and_b32_e32 v65, 0x7fffffff, v60
	v_and_b32_e32 v64, 0x7fffffff, v61
	v_cndmask_b32_e32 v50, v50, v57, vcc
	v_cmp_gt_i32_e32 vcc, 0, v54
	v_pk_add_f32 v[64:65], v[64:65], 0 neg_lo:[1,1] neg_hi:[1,1]
	s_waitcnt lgkmcnt(0)
	v_xor_b32_e32 v57, -1, v63
	v_cndmask_b32_e32 v51, v51, v53, vcc
	v_cmp_gt_i32_e32 vcc, s1, v84
	v_xor_b32_e32 v53, -1, v61
	s_add_i32 s1, s4, 0xfffff301
	v_cndmask_b32_e32 v55, 0, v51, vcc
	v_cmp_gt_i32_e32 vcc, s3, v84
	s_add_i32 s3, s4, 0xfffff2c1
	s_nop 0
	v_cndmask_b32_e32 v51, 0, v50, vcc
	v_cmp_gt_i32_e32 vcc, 0, v61
	v_xor_b32_e32 v50, -1, v60
	v_and_b32_e32 v61, 0x7fffffff, v62
	v_cndmask_b32_e32 v53, v64, v53, vcc
	v_cmp_gt_i32_e32 vcc, 0, v60
	v_and_b32_e32 v60, 0x7fffffff, v63
	v_pk_add_f32 v[60:61], v[60:61], 0 neg_lo:[1,1] neg_hi:[1,1]
	v_cndmask_b32_e32 v50, v65, v50, vcc
	v_cmp_gt_i32_e32 vcc, s1, v84
	s_add_i32 s1, s4, 0xfffff281
	s_nop 0
	v_cndmask_b32_e32 v54, 0, v50, vcc
	v_cmp_gt_i32_e32 vcc, s3, v84
	s_add_i32 s3, s4, 0xfffff241
	s_nop 0
	v_cndmask_b32_e32 v50, 0, v53, vcc
	v_cmp_gt_i32_e32 vcc, 0, v63
	v_xor_b32_e32 v53, -1, v62
	s_nop 0
	v_cndmask_b32_e32 v59, v60, v57, vcc
	v_cmp_gt_i32_e32 vcc, 0, v62
	s_nop 1
	v_cndmask_b32_e32 v53, v61, v53, vcc
	ds_read2st64_b32 v[60:61], v58 offset0:56 offset1:57
	v_cmp_gt_i32_e32 vcc, s1, v84
	ds_read2st64_b32 v[62:63], v58 offset0:58 offset1:59
	ds_read2st64_b32 v[66:67], v58 offset0:60 offset1:61
	ds_read2st64_b32 v[68:69], v58 offset0:62 offset1:63
	v_cndmask_b32_e32 v57, 0, v53, vcc
	v_cmp_gt_i32_e32 vcc, s3, v84
	s_waitcnt lgkmcnt(3)
	v_and_b32_e32 v58, 0x7fffffff, v61
	v_xor_b32_e32 v65, -1, v61
	v_cndmask_b32_e32 v53, 0, v59, vcc
	v_and_b32_e32 v59, 0x7fffffff, v60
	v_pk_add_f32 v[58:59], v[58:59], 0 neg_lo:[1,1] neg_hi:[1,1]
	v_cmp_gt_i32_e32 vcc, 0, v61
	v_xor_b32_e32 v64, -1, v60
	s_add_i32 s1, s4, 0xfffff201
	v_cndmask_b32_e32 v58, v58, v65, vcc
	v_cmp_gt_i32_e32 vcc, 0, v60
	s_add_i32 s3, s4, 0xfffff1c1
	s_waitcnt lgkmcnt(2)
	v_xor_b32_e32 v65, -1, v63
	v_cndmask_b32_e32 v59, v59, v64, vcc
	v_cmp_gt_i32_e32 vcc, s1, v84
	v_xor_b32_e32 v61, -1, v62
	s_add_i32 s1, s4, 0xfffff181
	v_cndmask_b32_e32 v64, 0, v59, vcc
	v_cmp_gt_i32_e32 vcc, s3, v84
	v_and_b32_e32 v59, 0x7fffffff, v62
	s_add_i32 s3, s4, 0xfffff141
	v_cndmask_b32_e32 v60, 0, v58, vcc
	v_and_b32_e32 v58, 0x7fffffff, v63
	v_pk_add_f32 v[58:59], v[58:59], 0 neg_lo:[1,1] neg_hi:[1,1]
	v_cmp_gt_i32_e32 vcc, 0, v63
	s_waitcnt lgkmcnt(1)
	v_and_b32_e32 v71, 0x7fffffff, v66
	v_and_b32_e32 v70, 0x7fffffff, v67
	v_cndmask_b32_e32 v58, v58, v65, vcc
	v_cmp_gt_i32_e32 vcc, 0, v62
	v_pk_add_f32 v[70:71], v[70:71], 0 neg_lo:[1,1] neg_hi:[1,1]
	s_waitcnt lgkmcnt(0)
	v_xor_b32_e32 v65, -1, v69
	v_cndmask_b32_e32 v59, v59, v61, vcc
	v_cmp_gt_i32_e32 vcc, s1, v84
	v_xor_b32_e32 v61, -1, v67
	s_add_i32 s1, s4, 0xfffff101
	v_cndmask_b32_e32 v63, 0, v59, vcc
	v_cmp_gt_i32_e32 vcc, s3, v84
	s_add_i32 s3, s4, 0xfffff0c1
	s_nop 0
	v_cndmask_b32_e32 v59, 0, v58, vcc
	v_cmp_gt_i32_e32 vcc, 0, v67
	v_xor_b32_e32 v58, -1, v66
	v_and_b32_e32 v67, 0x7fffffff, v68
	v_cndmask_b32_e32 v62, v70, v61, vcc
	v_cmp_gt_i32_e32 vcc, 0, v66
	v_and_b32_e32 v66, 0x7fffffff, v69
	v_pk_add_f32 v[66:67], v[66:67], 0 neg_lo:[1,1] neg_hi:[1,1]
	v_cndmask_b32_e32 v58, v71, v58, vcc
	v_cmp_gt_i32_e32 vcc, s1, v84
	s_add_i32 s1, s4, 0xfffff081
	s_nop 0
	v_cndmask_b32_e32 v61, 0, v58, vcc
	v_cmp_gt_i32_e32 vcc, s3, v84
	s_add_i32 s3, s4, 0xfffff041
	s_cmpk_lt_i32 s4, 0x100
	v_cndmask_b32_e32 v58, 0, v62, vcc
	v_cmp_gt_i32_e32 vcc, 0, v69
	v_xor_b32_e32 v62, -1, v68
	s_nop 0
	v_cndmask_b32_e32 v66, v66, v65, vcc
	v_cmp_gt_i32_e32 vcc, 0, v68
	s_nop 1
	v_cndmask_b32_e32 v62, v67, v62, vcc
	v_cmp_gt_i32_e32 vcc, s1, v84
	s_nop 1
	v_cndmask_b32_e32 v65, 0, v62, vcc
	v_cmp_gt_i32_e32 vcc, s3, v84
	s_nop 1
	v_cndmask_b32_e32 v62, 0, v66, vcc
	s_cbranch_scc1 .LBB0_1228
	s_cmp_gt_i32 s10, 7
	s_cselect_b64 s[0:1], -1, 0
	s_cmp_lt_i32 s10, 8
	s_cbranch_scc0 .LBB0_1229
	s_cmp_lg_u32 s10, 7
	s_cbranch_scc0 .LBB0_1231
	s_cmp_lt_i32 s10, 6
	s_cbranch_scc0 .LBB0_1233
	s_cmp_lg_u32 s10, 5
	s_cbranch_scc0 .LBB0_1234
	s_cmp_lt_i32 s10, 4
	s_cbranch_scc0 .LBB0_1235
	s_cmp_lg_u32 s10, 3
	s_cbranch_scc0 .LBB0_1236
	s_cmp_gt_i32 s10, 1
	s_cbranch_scc1 .LBB0_1237
	v_mov_b32_e32 v67, 31
	v_mov_b32_e32 v66, 0
